# rel-bias tables built from an LDS copy of the bias matrix instead of serialized global loads
# speedup vs baseline: 1.0101x; 1.0101x over previous
; __device__ __forceinline__ int otid() { int t = threadIdx.x; asm volatile("" : "+v"(t)); return t; }
; __device__ __forceinline__ void attn_phase(lptr L, const Params& P, int layer) {
;     const int tid = otid(), G = gridDim.x;
;     const int blk = (G % 8 == 0) ? (int)(blockIdx.x % 8) * (G / 8) + (int)(blockIdx.x / 8) : (int)blockIdx.x;
;     for (int i = tid; i < 16 * TABP; i += NT) {
;         const int h = i / TABP, d = i - h * TABP - TAB0;
;         float v = 0.f;
;         if (d >= 0) {
;             int bk = d;
;             if (d >= 16) { bk = (d >= 128) ? 31 : 16 + (int)(logf((float)d * (1.f / 16.f)) / logf(8.f) * 16.f); bk = bk > 31 ? 31 : bk; }
;             v = P.in[1][bk * 16 + h] * LOG2E;
;         }
;         lds_st<float>(L + A_TAB + i * 4, v);
.LBB0_137:
	v_writelane_b32 v255, s76, 55
	s_and_b64 vcc, exec, s[0:1]
	v_writelane_b32 v255, s84, 56
	s_cbranch_vccz .LBB0_745
	s_cmp_gt_i32 s76, 2
	s_mov_b64 s[2:3], -1
	s_cbranch_scc0 .LBB0_745
	s_cmp_gt_i32 s76, 4
	s_mov_b64 s[0:1], -1
	s_cbranch_scc0 .LBB0_691
	s_cmp_gt_i32 s76, 5
	s_cbranch_scc0 .LBB0_153
	v_readlane_b32 s2, v253, 8
	v_readlane_b32 s3, v253, 9
	v_lshlrev_b32_e32 v2, 2, v193
	s_nop 4
	global_load_dword v3, v2, s[2:3]
	s_waitcnt vmcnt(0)
	ds_write_b32 v2, v3
	s_waitcnt lgkmcnt(0)
	s_barrier
	v_mov_b32_e32 v0, v193
	s_movk_i32 s0, 0x1880
	s_nop 0
	v_cmp_gt_i32_e32 vcc, s0, v0
	s_and_saveexec_b64 s[0:1], vcc
	s_cbranch_execz .LBB0_150
	v_lshl_add_u32 v2, v0, 2, v219
	s_mov_b64 s[2:3], 0
	s_branch .LBB0_146

; __device__ __forceinline__ void attn_phase(lptr L, const Params& P, int layer) {
;     ...
;     for (int i = tid; i < 16 * TABP; i += NT) {
;         const int h = i / TABP, d = i - h * TABP - TAB0;
;         float v = 0.f;
;         if (d >= 0) {
;             int bk = d;
;             if (d >= 16) { bk = (d >= 128) ? 31 : 16 + (int)(logf((float)d * (1.f / 16.f)) / logf(8.f) * 16.f); bk = bk > 31 ? 31 : bk; }
;             v = P.in[1][bk * 16 + h] * LOG2E;
;         }
;         lds_st<float>(L + A_TAB + i * 4, v);
;     }
.LBB0_144:
	s_or_b64 exec, exec, s[26:27]
	v_lshl_add_u32 v4, v4, 4, v3
	v_readlane_b32 s56, v253, 6
	v_lshlrev_b32_e32 v4, 2, v4
	v_readlane_b32 s58, v253, 8
	v_readlane_b32 s59, v253, 9
	v_readlane_b32 s57, v253, 7
	v_readlane_b32 s60, v253, 10
	ds_read_b32 v3, v4
	v_readlane_b32 s61, v253, 11
	v_readlane_b32 s62, v253, 12
	v_readlane_b32 s63, v253, 13
	v_readlane_b32 s64, v253, 14
	v_readlane_b32 s65, v253, 15
	v_readlane_b32 s66, v253, 16
	v_readlane_b32 s67, v253, 17
	v_readlane_b32 s68, v253, 18
	v_readlane_b32 s69, v253, 19
	v_readlane_b32 s70, v253, 20
	v_readlane_b32 s71, v253, 21
	s_waitcnt lgkmcnt(0)
	v_mul_f32_e32 v4, 0x3fb8aa3b, v3
